# xblk page-table lookup via s_load instead of global_load+vmcnt0+readfirstlane
# speedup vs baseline: 1.0000x; 1.0000x over previous
; DI unsigned pk2(float lo, float hi) { f32x2 v = {lo, hi}; bf16x2_t b = __builtin_convertvector(v, bf16x2_t); return __builtin_bit_cast(unsigned, b); }
; DI void xblk_part(Frame& F, int rank, int nranks) {
;     ...
;     for (int it0 = gw * 4; it0 < NDB * 2048; it0 += NGW * 4) {
;         f32x4 v[4][2];
; #pragma unroll
;         for (int q = 0; q < 4; ++q) { const int it = it0 + q, s = it >> 11, row = it & 2047; const int page = F.ptab[s * 16 + (row >> 7)];
;             const float* src = F.c_cmp + ((size_t)page * 128 + (row & 127)) * 512;
;             v[q][0] = __builtin_nontemporal_load((const f32x4*)(src + 4 * lane)); v[q][1] = __builtin_nontemporal_load((const f32x4*)(src + 4 * (lane + 64))); }
; #pragma unroll
;         for (int q = 0; q < 4; ++q) { const int it = it0 + q, s = it >> 11, row = it & 2047;
; #pragma unroll
;             for (int j = 0; j < 2; ++j) { const int e = lane + 64 * j, kvsel = e >> 6, h = (e >> 4) & 3, d4 = (e & 15) * 4;
;                 u32x2 w; w.x = pk2(v[q][j][0], v[q][j][1]); w.y = pk2(v[q][j][2], v[q][j][3]);
;                 *(u32x2*)(F.XBLK + ((size_t)kvsel * XROWS + (size_t)(s * 4 + h) * 128 + (row >> 4)) * 1024 + (row & 15) * 64 + d4) = w; } }
;     }
.LBB0_89:
	s_ashr_i32 s0, s12, 7
	s_bfe_u32 s20, s12, 0x40007
	s_and_b32 s0, s0, -16
	s_or_b32 s20, s0, s20
	s_ashr_i32 s21, s20, 31
	s_lshl_b64 s[20:21], s[20:21], 2
	s_add_u32 s20, s48, s20
	s_addc_u32 s21, s49, s21
	s_load_dword s20, s[20:21], 0x0
	s_waitcnt lgkmcnt(0)
	s_ashr_i32 s21, s20, 31
	s_lshl_b64 s[20:21], s[20:21], 18
	s_add_u32 s0, s40, s20
	s_addc_u32 s21, s41, s21
	s_and_b32 s20, s18, 0xf800
	s_lshl_b32 s20, s20, 2
	s_add_u32 s20, s0, s20
	s_addc_u32 s21, s21, 0
	s_add_u32 s22, s20, 0x1000
	s_addc_u32 s23, s21, 0
	s_waitcnt lgkmcnt(0)
	global_load_dwordx4 v[8:11], v5, s[20:21] nt
	global_load_dwordx4 v[12:15], v5, s[20:21] offset:1024 nt
	global_load_dwordx4 v[16:19], v5, s[20:21] offset:2048 nt
	global_load_dwordx4 v[20:23], v5, s[20:21] offset:3072 nt
	s_add_u32 s20, s20, 0x1800
	global_load_dwordx4 v[24:27], v5, s[22:23] nt
	global_load_dwordx4 v[28:31], v6, s[22:23] nt
	s_addc_u32 s21, s21, 0
	global_load_dwordx4 v[32:35], v5, s[20:21] nt
	global_load_dwordx4 v[36:39], v6, s[20:21] nt
	s_ashr_i32 s20, s12, 9
	v_and_or_b32 v40, s20, -4, v4
	v_ashrrev_i32_e32 v41, 31, v40
	v_lshlrev_b64 v[40:41], 18, v[40:41]
	s_and_b32 s0, s14, 0x3f800
	s_lshl_b32 s22, s16, 1
	v_lshl_add_u64 v[40:41], s[62:63], 0, v[40:41]
	v_lshl_add_u64 v[40:41], v[40:41], 0, s[0:1]
	s_and_b32 s0, s22, 0x600
	v_lshl_add_u64 v[42:43], v[40:41], 0, s[0:1]
	v_lshl_add_u64 v[40:41], v[40:41], 0, s[10:11]
	s_mov_b32 s21, s1
	s_or_b32 s20, s0, 0x80
	v_lshl_add_u64 v[42:43], v[42:43], 0, v[2:3]
	v_lshl_add_u64 v[44:45], v[40:41], 0, s[0:1]
	v_lshl_add_u64 v[40:41], v[40:41], 0, v[2:3]
	s_mov_b32 s23, s1
	s_add_i32 s12, s12, s13
	s_add_i32 s14, s14, s15
	s_add_i32 s16, s16, s17
	s_add_i32 s18, s18, s19
	s_or_b32 s22, s0, 0x100
	s_or_b32 s0, s0, 0x180
	v_lshl_add_u64 v[44:45], v[44:45], 0, v[2:3]
	v_lshl_add_u64 v[46:47], v[40:41], 0, s[20:21]
	v_lshl_add_u64 v[48:49], v[40:41], 0, s[22:23]
	s_cmp_lt_i32 s12, 0x40000
	v_lshl_add_u64 v[40:41], v[40:41], 0, s[0:1]
	s_waitcnt vmcnt(7)
	v_cvt_pk_bf16_f32 v8, v8, v9
	v_cvt_pk_bf16_f32 v9, v10, v11
	s_waitcnt vmcnt(6)
	v_cvt_pk_bf16_f32 v10, v12, v13
	v_cvt_pk_bf16_f32 v11, v14, v15
	s_waitcnt vmcnt(5)
	v_cvt_pk_bf16_f32 v12, v16, v17
	v_cvt_pk_bf16_f32 v13, v18, v19
	s_waitcnt vmcnt(4)
	v_cvt_pk_bf16_f32 v14, v20, v21
	v_cvt_pk_bf16_f32 v15, v22, v23
	global_store_dwordx2 v[42:43], v[8:9], off
	global_store_dwordx2 v[44:45], v[10:11], off
	global_store_dwordx2 v[42:43], v[12:13], off offset:128
	global_store_dwordx2 v[46:47], v[14:15], off
	s_waitcnt vmcnt(7)
	v_cvt_pk_bf16_f32 v8, v24, v25
	v_cvt_pk_bf16_f32 v9, v26, v27
	s_waitcnt vmcnt(6)
	v_cvt_pk_bf16_f32 v10, v28, v29
	v_cvt_pk_bf16_f32 v11, v30, v31
	global_store_dwordx2 v[42:43], v[8:9], off offset:256
	global_store_dwordx2 v[48:49], v[10:11], off
	s_waitcnt vmcnt(7)
	v_cvt_pk_bf16_f32 v8, v32, v33
	v_cvt_pk_bf16_f32 v9, v34, v35
	s_waitcnt vmcnt(6)
	v_cvt_pk_bf16_f32 v10, v36, v37
	v_cvt_pk_bf16_f32 v11, v38, v39
	global_store_dwordx2 v[42:43], v[8:9], off offset:384
	global_store_dwordx2 v[40:41], v[10:11], off
	s_cbranch_scc1 .LBB0_89

; DI unsigned pk2(float lo, float hi) { f32x2 v = {lo, hi}; bf16x2_t b = __builtin_convertvector(v, bf16x2_t); return __builtin_bit_cast(unsigned, b); }
; DI void xblk_part(Frame& F, int rank, int nranks) {
;     ...
;     for (int it0 = gw * 4; it0 < NDB * 2048; it0 += NGW * 4) {
;         f32x4 v[4][2];
; #pragma unroll
;         for (int q = 0; q < 4; ++q) { const int it = it0 + q, s = it >> 11, row = it & 2047; const int page = F.ptab[s * 16 + (row >> 7)];
;             const float* src = F.c_cmp + ((size_t)page * 128 + (row & 127)) * 512;
;             v[q][0] = __builtin_nontemporal_load((const f32x4*)(src + 4 * lane)); v[q][1] = __builtin_nontemporal_load((const f32x4*)(src + 4 * (lane + 64))); }
; #pragma unroll
;         for (int q = 0; q < 4; ++q) { const int it = it0 + q, s = it >> 11, row = it & 2047;
; #pragma unroll
;             for (int j = 0; j < 2; ++j) { const int e = lane + 64 * j, kvsel = e >> 6, h = (e >> 4) & 3, d4 = (e & 15) * 4;
;                 u32x2 w; w.x = pk2(v[q][j][0], v[q][j][1]); w.y = pk2(v[q][j][2], v[q][j][3]);
;                 *(u32x2*)(F.XBLK + ((size_t)kvsel * XROWS + (size_t)(s * 4 + h) * 128 + (row >> 4)) * 1024 + (row & 15) * 64 + d4) = w; } }
;     }
.LBB0_110:
	s_ashr_i32 s0, s8, 7
	s_bfe_u32 s16, s8, 0x40007
	s_and_b32 s0, s0, -16
	s_or_b32 s16, s0, s16
	s_ashr_i32 s17, s16, 31
	s_lshl_b64 s[16:17], s[16:17], 2
	s_add_u32 s16, s48, s16
	s_addc_u32 s17, s49, s17
	s_load_dword s16, s[16:17], 0x0
	s_waitcnt lgkmcnt(0)
	s_ashr_i32 s17, s16, 31
	s_lshl_b64 s[16:17], s[16:17], 18
	s_add_u32 s0, s40, s16
	s_addc_u32 s17, s41, s17
	s_and_b32 s16, s14, 0xf800
	s_lshl_b32 s16, s16, 2
	s_add_u32 s16, s0, s16
	s_addc_u32 s17, s17, 0
	s_add_u32 s18, s16, 0x1000
	s_addc_u32 s19, s17, 0
	global_load_dwordx4 v[8:11], v5, s[16:17] nt
	global_load_dwordx4 v[12:15], v5, s[16:17] offset:1024 nt
	global_load_dwordx4 v[16:19], v5, s[16:17] offset:2048 nt
	global_load_dwordx4 v[20:23], v5, s[16:17] offset:3072 nt
	s_add_u32 s16, s16, 0x1800
	global_load_dwordx4 v[24:27], v5, s[18:19] nt
	global_load_dwordx4 v[28:31], v6, s[18:19] nt
	s_addc_u32 s17, s17, 0
	global_load_dwordx4 v[32:35], v5, s[16:17] nt
	global_load_dwordx4 v[36:39], v6, s[16:17] nt
	s_ashr_i32 s16, s8, 9
	v_and_or_b32 v40, s16, -4, v4
	v_ashrrev_i32_e32 v41, 31, v40
	v_lshlrev_b64 v[40:41], 18, v[40:41]
	s_and_b32 s0, s10, 0x3f800
	s_lshl_b32 s18, s12, 1
	v_lshl_add_u64 v[40:41], s[62:63], 0, v[40:41]
	v_lshl_add_u64 v[40:41], v[40:41], 0, s[0:1]
	s_and_b32 s0, s18, 0x600
	v_lshl_add_u64 v[42:43], v[40:41], 0, s[0:1]
	v_lshl_add_u64 v[40:41], v[40:41], 0, s[6:7]
	s_mov_b32 s17, s1
	s_or_b32 s16, s0, 0x80
	v_lshl_add_u64 v[42:43], v[42:43], 0, v[2:3]
	v_lshl_add_u64 v[44:45], v[40:41], 0, s[0:1]
	v_lshl_add_u64 v[40:41], v[40:41], 0, v[2:3]
	s_mov_b32 s19, s1
	s_add_i32 s8, s8, s9
	s_add_i32 s10, s10, s11
	s_add_i32 s12, s12, s13
	s_add_i32 s14, s14, s15
	s_or_b32 s18, s0, 0x100
	s_or_b32 s0, s0, 0x180
	v_lshl_add_u64 v[44:45], v[44:45], 0, v[2:3]
	v_lshl_add_u64 v[46:47], v[40:41], 0, s[16:17]
	v_lshl_add_u64 v[48:49], v[40:41], 0, s[18:19]
	s_cmp_lt_i32 s8, 0x40000
	v_lshl_add_u64 v[40:41], v[40:41], 0, s[0:1]
	s_waitcnt vmcnt(7)
	v_cvt_pk_bf16_f32 v8, v8, v9
	v_cvt_pk_bf16_f32 v9, v10, v11
	s_waitcnt vmcnt(6)
	v_cvt_pk_bf16_f32 v10, v12, v13
	v_cvt_pk_bf16_f32 v11, v14, v15
	s_waitcnt vmcnt(5)
	v_cvt_pk_bf16_f32 v12, v16, v17
	v_cvt_pk_bf16_f32 v13, v18, v19
	s_waitcnt vmcnt(4)
	v_cvt_pk_bf16_f32 v14, v20, v21
	v_cvt_pk_bf16_f32 v15, v22, v23
	global_store_dwordx2 v[42:43], v[8:9], off
	global_store_dwordx2 v[44:45], v[10:11], off
	global_store_dwordx2 v[42:43], v[12:13], off offset:128
	global_store_dwordx2 v[46:47], v[14:15], off
	s_waitcnt vmcnt(7)
	v_cvt_pk_bf16_f32 v8, v24, v25
	v_cvt_pk_bf16_f32 v9, v26, v27
	s_waitcnt vmcnt(6)
	v_cvt_pk_bf16_f32 v10, v28, v29
	v_cvt_pk_bf16_f32 v11, v30, v31
	global_store_dwordx2 v[42:43], v[8:9], off offset:256
	global_store_dwordx2 v[48:49], v[10:11], off
	s_waitcnt vmcnt(7)
	v_cvt_pk_bf16_f32 v8, v32, v33
	v_cvt_pk_bf16_f32 v9, v34, v35
	s_waitcnt vmcnt(6)
	v_cvt_pk_bf16_f32 v10, v36, v37
	v_cvt_pk_bf16_f32 v11, v38, v39
	global_store_dwordx2 v[42:43], v[8:9], off offset:384
	global_store_dwordx2 v[40:41], v[10:11], off
	s_cbranch_scc1 .LBB0_110
